# attention KV loop software-pipelined inside each wave: next-tile mask init under P.V MFMAs, P1 init and exp(P0) under QK MFMAs, exp(P1) under first P.V half, all K fragments prefetched; S4 gather 16 l
# speedup vs baseline: 1.0920x; 1.0155x over previous
; #define LAS __attribute__((address_space(3)))
; __device__ __forceinline__ void attn_unit(const AttArgs& a, int b, int h, int qb, LAS unsigned char* shm, int tid) {
;     ...
;     const bf16* Qw = a.Q + (rowb + q0 + wave * 32) * 512 + h * 64;
;     const bf16* Kh = a.K + rowb * 256 + n * 64; const bf16* Vh = a.V + rowb * 256 + n * 64;
;     const bf16* ksrc = Kh + (size_t)lane * 256 + wave * 8;
;     const bf16* vsrc = Vh + (size_t)(16 * (wave & 3) + (lane >> 2)) * 256 + (wave >> 2) * 32 + (lane & 3) * 8;
;     const u64* mrow = a.MASK + (size_t)b * NT64 * SEQ + q0 + wave * 32 + r32;
;     LAS float* wsf = (LAS float*)(shm + AT_WS) + wave * 64;
;     bf16x8 qr[4];
; #pragma unroll
;     for (int d0 = 0; d0 < 4; ++d0) qr[d0] = *(const bf16x8*)(Qw + (size_t)r32 * 512 + d0 * 16 + hi * 8);
;     f32x16 o[2]; o[0] = f32x16{}; o[1] = f32x16{}; float m_run = 0.f, l_run = 0.f;
;     u32x4_t kr[2], vr[2]; u64 mwr[2];
;     kr[0] = *(const u32x4_t*)ksrc; vr[0] = *(const u32x4_t*)vsrc; mwr[0] = mrow[0];
;     kr[1] = *(const u32x4_t*)(ksrc + (size_t)64 * 256); vr[1] = *(const u32x4_t*)(vsrc + (size_t)64 * 256); mwr[1] = mrow[SEQ];
;     *(LAS u32x4_t*)(shm + AT_KV + wave * 1024 + lane * 16) = kr[0]; *(LAS u32x4_t*)(shm + AT_KV + 8192 + wave * 1024 + lane * 16) = vr[0];
;     __syncthreads();
;     for (int t2 = 0; t2 < NT; t2 += 2) {
; #pragma unroll
;       for (int par = 0; par < 2; ++par) { const int t = t2 + par;
;         LAS unsigned char* Kb = shm + AT_KV + par * 16384; LAS unsigned char* Vb = Kb + 8192; const u64 mw = mwr[par];
;         if (t + 2 < NT) { kr[par] = *(const u32x4_t*)(ksrc + (size_t)(t + 2) * 64 * 256); vr[par] = *(const u32x4_t*)(vsrc + (size_t)(t + 2) * 64 * 256); mwr[par] = mrow[(size_t)(t + 2) * SEQ]; }
;         f32x16 p0, p1;
;         { const unsigned nm0 = ~((unsigned)mw >> (4 * hi)), nm1 = ~((unsigned)(mw >> 32) >> (4 * hi)), nb = __float_as_uint(-m_run);
; #pragma unroll
;           for (int r = 0; r < 16; ++r) { const int bit = (r & 3) + 8 * (r >> 2); const unsigned t0 = (unsigned)__builtin_amdgcn_sbfe((int)nm0, bit, 1), t1 = (unsigned)__builtin_amdgcn_sbfe((int)nm1, bit, 1);
;               p0[r] = __uint_as_float((t0 & 0xff800000u) | (~t0 & nb)); p1[r] = __uint_as_float((t1 & 0xff800000u) | (~t1 & nb)); } }
;         { LAS unsigned char* kb = Kb + hi * 1024 + r32 * 16;
; #pragma unroll
.LBB0_1065:
	v_readfirstlane_b32 s34, v99
	s_ashr_i32 s24, s34, 6
	s_and_b64 s[6:7], s[2:3], exec
	s_cselect_b32 s16, s11, s20
	s_lshl_b32 s14, s24, 5
	s_add_i32 s35, s16, 0x100
	s_or_b32 s6, s10, s16
	s_ashr_i32 s15, s14, 31
	s_add_u32 s6, s6, s14
	s_addc_u32 s7, 0, s15
	s_lshl_b32 s17, s24, 4
	v_and_or_b32 v3, s17, 48, v150
	s_ashr_i32 s17, s34, 3
	s_lshl_b32 s26, s24, 3
	s_and_b32 s28, s17, 0xffffffe0
	s_lshl_b64 s[18:19], s[6:7], 10
	s_ashr_i32 s27, s26, 31
	s_ashr_i32 s29, s28, 31
	s_lshl_b32 s36, s16, 3
	s_add_u32 s25, s21, s36
	s_addc_u32 s30, s22, 0
	s_lshl_b64 s[16:17], s[14:15], 3
	s_add_u32 s14, s25, s16
	v_lshlrev_b32_e32 v16, 9, v3
	v_mov_b32_e32 v17, v215
	s_addc_u32 s15, s30, s17
	s_lshl_b64 s[30:31], s[26:27], 1
	v_lshl_add_u64 v[6:7], s[0:1], 0, v[16:17]
	s_lshl_b64 s[28:29], s[28:29], 1
	v_lshl_add_u64 v[4:5], v[122:123], 0, s[30:31]
	v_lshl_add_u64 v[6:7], v[6:7], 0, s[28:29]
	v_mov_b32_e32 v113, v215
	v_lshl_add_u64 v[6:7], v[6:7], 0, v[112:113]
	global_load_dwordx4 v[82:85], v[4:5], off
	global_load_dwordx4 v[86:89], v[6:7], off
	v_lshl_add_u64 v[10:11], v[120:121], 0, s[18:19]
	v_add_co_u32_e32 v4, vcc, s33, v4
	global_load_dwordx4 v[66:69], v[10:11], off
	global_load_dwordx4 v[70:73], v[10:11], off offset:32
	global_load_dwordx4 v[74:77], v[10:11], off offset:64
	global_load_dwordx4 v[78:81], v[10:11], off offset:96
	v_addc_co_u32_e32 v5, vcc, 0, v5, vcc
	v_lshlrev_b32_e32 v2, 3, v98
	v_mov_b32_e32 v3, v215
	v_add_co_u32_e32 v6, vcc, s33, v6
	v_lshl_add_u64 v[8:9], s[14:15], 0, v[2:3]
	s_nop 0
	v_addc_co_u32_e32 v7, vcc, 0, v7, vcc
	v_add_co_u32_e32 v8, vcc, s33, v8
	s_and_b32 s18, s34, 0x3fffffc0
	s_nop 0
	v_addc_co_u32_e32 v9, vcc, 0, v9, vcc
	global_load_dwordx2 v[34:35], v2, s[14:15]
	global_load_dwordx2 v[140:141], v[8:9], off
	global_load_dwordx4 v[90:93], v[4:5], off
	global_load_dwordx4 v[94:97], v[6:7], off
	s_lshl_b32 s18, s18, 2
	s_lshr_b32 s26, s35, 6
	s_lshl_b32 s19, s24, 10
	s_add_i32 s18, s18, 0
	s_add_u32 s16, s16, s36
	v_mov_b32_e32 v119, 0
	v_lshl_add_u64 v[16:17], s[28:29], 0, v[16:17]
	s_addc_u32 s17, s17, 0
	s_mov_b32 s25, 3
	s_mov_b64 s[14:15], 0
	v_mov_b32_e32 v113, 0
	v_mov_b32_e32 v2, 0
	v_mov_b32_e32 v3, v119
	v_mov_b32_e32 v4, v119
	v_mov_b32_e32 v5, v119
	v_mov_b32_e32 v6, v119
	v_mov_b32_e32 v7, v119
	v_mov_b32_e32 v8, v119
	v_mov_b32_e32 v9, v119
	v_mov_b32_e32 v10, v119
	v_mov_b32_e32 v11, v119
	v_mov_b32_e32 v12, v119
	v_mov_b32_e32 v13, v119
	v_mov_b32_e32 v14, v119
	v_mov_b32_e32 v15, v119
	v_add_u32_e32 v117, s19, v151
	v_lshl_add_u64 v[132:133], v[126:127], 0, s[30:31]
	v_lshl_add_u64 v[134:135], v[128:129], 0, v[16:17]
	v_lshl_add_u32 v115, v98, 2, s18
	v_lshl_add_u32 v111, v152, 2, s18
	v_lshl_add_u64 v[136:137], v[130:131], 0, s[16:17]
	v_mov_b32_e32 v16, v119
	v_mov_b32_e32 v17, v119
	v_mov_b32_e32 v18, 0
	v_mov_b32_e32 v19, v119
	v_mov_b32_e32 v20, v119
	v_mov_b32_e32 v21, v119
	v_mov_b32_e32 v22, v119
	v_mov_b32_e32 v23, v119
	v_mov_b32_e32 v24, v119
	v_mov_b32_e32 v25, v119
	v_mov_b32_e32 v26, v119
	v_mov_b32_e32 v27, v119
	v_mov_b32_e32 v28, v119
	v_mov_b32_e32 v29, v119
	v_mov_b32_e32 v30, v119
	v_mov_b32_e32 v31, v119
	v_mov_b32_e32 v32, v119
	v_mov_b32_e32 v33, v119
	s_waitcnt vmcnt(9)
	ds_write_b128 v117, v[82:85]
	s_waitcnt vmcnt(8)
	ds_write_b128 v117, v[86:89] offset:8192
	s_waitcnt lgkmcnt(0)
	s_barrier
	s_waitcnt vmcnt(3)
	v_mov_b64_e32 v[138:139], v[34:35]
	v_xor_b32_e32 v177, 0x80000000, v113
	v_lshrrev_b32_e32 v50, v152, v35
	v_lshrrev_b32_e32 v34, v152, v34
	v_bfe_i32 v49, v34, 27, 1
	v_bfe_i32 v48, v34, 26, 1
	v_bfe_i32 v47, v34, 25, 1
	v_bfe_i32 v46, v34, 24, 1
	v_bfe_i32 v45, v34, 19, 1
	v_bfe_i32 v44, v34, 18, 1
	v_bfe_i32 v43, v34, 17, 1
	v_bfe_i32 v42, v34, 16, 1
	v_bfe_i32 v41, v34, 11, 1
	v_bfe_i32 v40, v34, 10, 1
	v_bfe_i32 v39, v34, 9, 1
	v_bfe_i32 v38, v34, 8, 1
	v_bfe_i32 v37, v34, 3, 1
	v_bfe_i32 v36, v34, 2, 1
	v_bfe_i32 v35, v34, 1, 1
	v_bfe_i32 v34, v34, 0, 1
	v_bfi_b32 v49, v49, v177, v245
	v_bfi_b32 v48, v48, v177, v245
	v_bfi_b32 v47, v47, v177, v245
	v_bfi_b32 v46, v46, v177, v245
	v_bfi_b32 v45, v45, v177, v245
	v_bfi_b32 v44, v44, v177, v245
	v_bfi_b32 v43, v43, v177, v245
	v_bfi_b32 v42, v42, v177, v245
	v_bfi_b32 v41, v41, v177, v245
	v_bfi_b32 v40, v40, v177, v245
	v_bfi_b32 v39, v39, v177, v245
	v_bfi_b32 v38, v38, v177, v245
	v_bfi_b32 v37, v37, v177, v245
	v_bfi_b32 v36, v36, v177, v245
	v_bfi_b32 v35, v35, v177, v245
	v_bfi_b32 v34, v34, v177, v245
.LBB0_1066:
	s_add_i32 s27, s25, -1
	s_cmp_lt_u32 s27, s26
	s_cselect_b64 s[16:17], -1, 0
	s_and_b64 vcc, exec, s[16:17]
	ds_read_b128 v[178:181], v176
	ds_read_b128 v[182:185], v176 offset:2048
	ds_read_b128 v[186:189], v176 offset:4096
	ds_read_b128 v[192:195], v176 offset:6144
	ds_read_b128 v[196:199], v176 offset:512
	ds_read_b128 v[200:203], v176 offset:2560
	ds_read_b128 v[204:207], v176 offset:4608
	ds_read_b128 v[208:211], v176 offset:6656
	v_lshl_add_u64 v[146:147], v[132:133], 0, s[14:15]
	v_lshl_add_u64 v[144:145], v[134:135], 0, s[14:15]
	v_lshl_add_u64 v[142:143], v[136:137], 0, s[14:15]
	s_cbranch_vccz .LBB0_1068
	v_add_co_u32_e32 v148, vcc, 0x1df10000, v146
	s_nop 1
	v_addc_co_u32_e32 v149, vcc, 0, v147, vcc
	v_add_co_u32_e32 v212, vcc, 0x1e710000, v144
	s_nop 1
	v_addc_co_u32_e32 v213, vcc, 0, v145, vcc
	global_load_dwordx4 v[82:85], v[148:149], off
	global_load_dwordx4 v[86:89], v[212:213], off
	v_add_co_u32_e32 v148, vcc, 0x1c710000, v142
	s_nop 1
	v_addc_co_u32_e32 v149, vcc, 0, v143, vcc
	global_load_dwordx2 v[138:139], v[148:149], off
; #define LAS __attribute__((address_space(3)))
; __device__ __forceinline__ void attn_unit(const AttArgs& a, int b, int h, int qb, LAS unsigned char* shm, int tid) {
;     ...
;         { const unsigned nm0 = ~((unsigned)mw >> (4 * hi)), nm1 = ~((unsigned)(mw >> 32) >> (4 * hi)), nb = __float_as_uint(-m_run);
; #pragma unroll
;           for (int r = 0; r < 16; ++r) { const int bit = (r & 3) + 8 * (r >> 2); const unsigned t0 = (unsigned)__builtin_amdgcn_sbfe((int)nm0, bit, 1), t1 = (unsigned)__builtin_amdgcn_sbfe((int)nm1, bit, 1);
;               p0[r] = __uint_as_float((t0 & 0xff800000u) | (~t0 & nb)); p1[r] = __uint_as_float((t1 & 0xff800000u) | (~t1 & nb)); } }
;         { LAS unsigned char* kb = Kb + hi * 1024 + r32 * 16;
; #pragma unroll
;           for (int d0 = 0; d0 < 4; ++d0) { const bf16x8 k0 = *(const LAS bf16x8*)(kb + d0 * 2048), k1 = *(const LAS bf16x8*)(kb + d0 * 2048 + 512);
;               p0 = __builtin_amdgcn_mfma_f32_32x32x16_bf16(k0, qr[d0], p0, 0, 0, 0); p1 = __builtin_amdgcn_mfma_f32_32x32x16_bf16(k1, qr[d0], p1, 0, 0, 0); } }
.LBB0_1068:
	v_bfe_i32 v65, v50, 27, 1
	v_bfe_i32 v64, v50, 26, 1
	v_bfe_i32 v63, v50, 25, 1
	v_bfe_i32 v62, v50, 24, 1
	v_bfe_i32 v61, v50, 19, 1
	v_bfe_i32 v60, v50, 18, 1
	v_bfe_i32 v59, v50, 17, 1
	v_bfe_i32 v58, v50, 16, 1
	s_waitcnt lgkmcnt(7)
	v_mfma_f32_32x32x16_bf16 v[34:49], v[178:181], v[66:69], v[34:49]
	v_bfe_i32 v57, v50, 11, 1
	v_bfe_i32 v56, v50, 10, 1
	v_bfe_i32 v55, v50, 9, 1
	v_bfe_i32 v54, v50, 8, 1
	v_bfe_i32 v53, v50, 3, 1
	v_bfe_i32 v52, v50, 2, 1
	v_bfe_i32 v51, v50, 1, 1
	v_bfe_i32 v50, v50, 0, 1
	s_waitcnt lgkmcnt(6)
	v_mfma_f32_32x32x16_bf16 v[34:49], v[182:185], v[70:73], v[34:49]
	v_bfi_b32 v65, v65, v177, v245
	v_bfi_b32 v64, v64, v177, v245
	v_bfi_b32 v63, v63, v177, v245
	v_bfi_b32 v62, v62, v177, v245
	v_bfi_b32 v61, v61, v177, v245
	v_bfi_b32 v60, v60, v177, v245
	v_bfi_b32 v59, v59, v177, v245
	v_bfi_b32 v58, v58, v177, v245
	s_waitcnt lgkmcnt(5)
	v_mfma_f32_32x32x16_bf16 v[34:49], v[186:189], v[74:77], v[34:49]
	v_bfi_b32 v57, v57, v177, v245
	v_bfi_b32 v56, v56, v177, v245
	v_bfi_b32 v55, v55, v177, v245
	v_bfi_b32 v54, v54, v177, v245
	v_bfi_b32 v53, v53, v177, v245
	v_bfi_b32 v52, v52, v177, v245
	v_bfi_b32 v51, v51, v177, v245
	v_bfi_b32 v50, v50, v177, v245
	s_waitcnt lgkmcnt(4)
	v_mfma_f32_32x32x16_bf16 v[34:49], v[192:195], v[78:81], v[34:49]
	ds_read_b64_tr_b16 v[178:179],v153 offset:0
	ds_read_b64_tr_b16 v[180:181],v153 offset:512
	ds_read_b64_tr_b16 v[182:183],v153 offset:4096
	ds_read_b64_tr_b16 v[184:185],v153 offset:4608
	ds_read_b64_tr_b16 v[186:187],v153 offset:1024
	ds_read_b64_tr_b16 v[188:189],v153 offset:1536
	ds_read_b64_tr_b16 v[192:193],v153 offset:5120
	ds_read_b64_tr_b16 v[194:195],v153 offset:5632
	s_cmp_lg_u32 s14, 0
	s_cbranch_scc0 .Latt_t0
	s_waitcnt lgkmcnt(11)
	v_mfma_f32_32x32x16_bf16 v[50:65], v[196:199], v[66:69], v[50:65]
	s_nop 3
	v_exp_f32_e32 v34, v34
	v_exp_f32_e32 v35, v35
	v_exp_f32_e32 v36, v36
	v_exp_f32_e32 v37, v37
	s_waitcnt lgkmcnt(10)
	v_mfma_f32_32x32x16_bf16 v[50:65], v[200:203], v[70:73], v[50:65]
	v_exp_f32_e32 v38, v38
	v_exp_f32_e32 v39, v39
	v_exp_f32_e32 v40, v40
	v_exp_f32_e32 v41, v41
	s_waitcnt lgkmcnt(9)
	v_mfma_f32_32x32x16_bf16 v[50:65], v[204:207], v[74:77], v[50:65]
	v_exp_f32_e32 v42, v42
	v_exp_f32_e32 v43, v43
	v_exp_f32_e32 v44, v44
	v_exp_f32_e32 v45, v45
	s_waitcnt lgkmcnt(8)
	v_mfma_f32_32x32x16_bf16 v[50:65], v[208:211], v[78:81], v[50:65]
	v_exp_f32_e32 v46, v46
	v_exp_f32_e32 v47, v47
	v_exp_f32_e32 v48, v48
	v_exp_f32_e32 v49, v49
; __device__ __forceinline__ void attn_unit(const AttArgs& a, int b, int h, int qb, LAS unsigned char* shm, int tid) {
;     ...
;         float rs;
;         { typedef float f32x2_t __attribute__((ext_vector_type(2))); f32x2_t rs2 = {0.f, 0.f};
; #pragma unroll
;           for (int r = 0; r < 16; ++r) { p0[r] = __builtin_amdgcn_exp2f(p0[r]); p1[r] = __builtin_amdgcn_exp2f(p1[r]); rs2 += (f32x2_t){p0[r], p1[r]}; }
;           rs = rs2[0] + rs2[1]; l_run += rs; }
;         const bool regrow = __any(rs > 1.0995e12f);
;         u32x4_t pw0, pw1, pw2, pw3;
;         pw0 = (u32x4_t){cvtpk(p0[0], p0[1]), cvtpk(p0[2], p0[3]), cvtpk(p0[4], p0[5]), cvtpk(p0[6], p0[7])}; pw1 = (u32x4_t){cvtpk(p0[8], p0[9]), cvtpk(p0[10], p0[11]), cvtpk(p0[12], p0[13]), cvtpk(p0[14], p0[15])};
;         pw2 = (u32x4_t){cvtpk(p1[0], p1[1]), cvtpk(p1[2], p1[3]), cvtpk(p1[4], p1[5]), cvtpk(p1[6], p1[7])}; pw3 = (u32x4_t){cvtpk(p1[8], p1[9]), cvtpk(p1[10], p1[11]), cvtpk(p1[12], p1[13]), cvtpk(p1[14], p1[15])};
;         { const unsigned vb = (unsigned)(uintptr_t)Vb + ((lane >> 4) & 1) * 32 + (lane & 3) * 8 + (4 * hi + ((lane & 15) >> 2)) * 64;
; #pragma unroll
;           for (int d0 = 0; d0 < 2; ++d0) { s16x4 lo[4], hh[4];
; #pragma unroll
;               for (int ks = 0; ks < 4; ++ks) {
;                   asm volatile("ds_read_b64_tr_b16 %0,%1 offset:%c2" : "=&v"(lo[ks]) : "v"(vb), "i"(d0 * 4096 + ks * 1024) : "memory");
;                   asm volatile("ds_read_b64_tr_b16 %0,%1 offset:%c2" : "=&v"(hh[ks]) : "v"(vb), "i"(d0 * 4096 + ks * 1024 + 512) : "memory"); }
;               asm volatile("s_waitcnt lgkmcnt(0)" ::: "memory"); __builtin_amdgcn_sched_barrier(0);
;     ...
;               o[d0] = __builtin_amdgcn_mfma_f32_32x32x16_bf16(__builtin_bit_cast(bf16x8, pw0), DSA_PK(0), o[d0], 0, 0, 0);
;               o[d0] = __builtin_amdgcn_mfma_f32_32x32x16_bf16(__builtin_bit_cast(bf16x8, pw1), DSA_PK(1), o[d0], 0, 0, 0);
;               o[d0] = __builtin_amdgcn_mfma_f32_32x32x16_bf16(__builtin_bit_cast(bf16x8, pw2), DSA_PK(2), o[d0], 0, 0, 0);
;               o[d0] = __builtin_amdgcn_mfma_f32_32x32x16_bf16(__builtin_bit_cast(bf16x8, pw3), DSA_PK(3), o[d0], 0, 0, 0);
;     ...
;           } }
;         if (regrow) { const float rsf = __builtin_amdgcn_fmed3f(rs, __shfl_xor(rs, 32), INFINITY); const float dl = rsf > 1.0995e12f ? floorf(__log2f(rsf)) : 0.f;
.Latt_j0:
	v_cvt_pk_bf16_f32 v196, v34, v35
	v_pk_add_f32 v[212:213], v[34:35], v[36:37]
	v_cvt_pk_bf16_f32 v197, v36, v37
	v_pk_add_f32 v[212:213], v[38:39], v[212:213]
	v_cvt_pk_bf16_f32 v198, v38, v39
	v_pk_add_f32 v[212:213], v[40:41], v[212:213]
	v_cvt_pk_bf16_f32 v199, v40, v41
	v_pk_add_f32 v[212:213], v[42:43], v[212:213]
	v_cvt_pk_bf16_f32 v200, v42, v43
	v_pk_add_f32 v[212:213], v[44:45], v[212:213]
	v_cvt_pk_bf16_f32 v201, v44, v45
	v_pk_add_f32 v[212:213], v[46:47], v[212:213]
	v_cvt_pk_bf16_f32 v202, v46, v47
	v_pk_add_f32 v[212:213], v[48:49], v[212:213]
	v_cvt_pk_bf16_f32 v203, v48, v49
	s_waitcnt lgkmcnt(0)
	v_mfma_f32_32x32x16_bf16 v[2:17], v[196:199], v[178:181], v[2:17]
	ds_read_b64_tr_b16 v[178:179],v153 offset:2048
	ds_read_b64_tr_b16 v[180:181],v153 offset:2560
	v_exp_f32_e32 v50, v50
	v_exp_f32_e32 v51, v51
	v_exp_f32_e32 v52, v52
	v_exp_f32_e32 v53, v53
	v_mfma_f32_32x32x16_bf16 v[18:33], v[196:199], v[182:185], v[18:33]
	ds_read_b64_tr_b16 v[182:183],v153 offset:6144
	ds_read_b64_tr_b16 v[184:185],v153 offset:6656
	v_exp_f32_e32 v54, v54
	v_exp_f32_e32 v55, v55
	v_exp_f32_e32 v56, v56
	v_exp_f32_e32 v57, v57
	v_mfma_f32_32x32x16_bf16 v[2:17], v[200:203], v[186:189], v[2:17]
	ds_read_b64_tr_b16 v[186:187],v153 offset:3072
	ds_read_b64_tr_b16 v[188:189],v153 offset:3584
	v_exp_f32_e32 v58, v58
	v_exp_f32_e32 v59, v59
	v_exp_f32_e32 v60, v60
	v_exp_f32_e32 v61, v61
	v_mfma_f32_32x32x16_bf16 v[18:33], v[200:203], v[192:195], v[18:33]
	ds_read_b64_tr_b16 v[192:193],v153 offset:7168
	ds_read_b64_tr_b16 v[194:195],v153 offset:7680
	v_exp_f32_e32 v62, v62
	v_exp_f32_e32 v63, v63
	v_exp_f32_e32 v64, v64
	v_exp_f32_e32 v65, v65
	v_cvt_pk_bf16_f32 v204, v50, v51
	v_cvt_pk_bf16_f32 v205, v52, v53
	v_cvt_pk_bf16_f32 v206, v54, v55
	v_cvt_pk_bf16_f32 v207, v56, v57
	v_cvt_pk_bf16_f32 v208, v58, v59
	v_cvt_pk_bf16_f32 v209, v60, v61
	v_cvt_pk_bf16_f32 v210, v62, v63
	v_cvt_pk_bf16_f32 v211, v64, v65
	v_pk_add_f32 v[212:213], v[50:51], v[212:213]
	v_pk_add_f32 v[212:213], v[52:53], v[212:213]
	v_pk_add_f32 v[212:213], v[54:55], v[212:213]
	v_pk_add_f32 v[212:213], v[56:57], v[212:213]
	v_pk_add_f32 v[212:213], v[58:59], v[212:213]
	v_pk_add_f32 v[212:213], v[60:61], v[212:213]
	v_pk_add_f32 v[212:213], v[62:63], v[212:213]
	v_pk_add_f32 v[212:213], v[64:65], v[212:213]
	v_add_f32_e32 v212, v212, v213
	v_cmp_lt_f32_e32 vcc, s61, v212
	v_add_f32_e32 v119, v119, v212
	s_waitcnt lgkmcnt(6)
	v_mfma_f32_32x32x16_bf16 v[2:17], v[204:207], v[178:181], v[2:17]
	s_waitcnt vmcnt(3)
	v_lshrrev_b32_e32 v34, v152, v140
	v_xor_b32_e32 v177, 0x80000000, v113
	v_bfe_i32 v49, v34, 27, 1
	v_bfe_i32 v48, v34, 26, 1
	v_bfe_i32 v47, v34, 25, 1
	v_bfe_i32 v46, v34, 24, 1
	v_bfe_i32 v45, v34, 19, 1
	v_bfe_i32 v44, v34, 18, 1
	s_waitcnt lgkmcnt(4)
	v_mfma_f32_32x32x16_bf16 v[18:33], v[204:207], v[182:185], v[18:33]
	v_bfe_i32 v43, v34, 17, 1
	v_bfe_i32 v42, v34, 16, 1
	v_bfe_i32 v41, v34, 11, 1
	v_bfe_i32 v40, v34, 10, 1
	v_bfe_i32 v39, v34, 9, 1
	v_bfe_i32 v38, v34, 8, 1
	v_bfe_i32 v37, v34, 3, 1
	v_bfe_i32 v36, v34, 2, 1
	v_bfe_i32 v35, v34, 1, 1
	s_waitcnt lgkmcnt(2)
	v_mfma_f32_32x32x16_bf16 v[2:17], v[208:211], v[186:189], v[2:17]
	v_bfe_i32 v34, v34, 0, 1
	v_bfi_b32 v49, v49, v177, v245
	v_bfi_b32 v48, v48, v177, v245
	v_bfi_b32 v47, v47, v177, v245
	v_bfi_b32 v46, v46, v177, v245
	v_bfi_b32 v45, v45, v177, v245
	v_bfi_b32 v44, v44, v177, v245
	v_bfi_b32 v43, v43, v177, v245
	v_bfi_b32 v42, v42, v177, v245
	s_waitcnt lgkmcnt(0)
	v_mfma_f32_32x32x16_bf16 v[18:33], v[208:211], v[192:195], v[18:33]
	v_bfi_b32 v41, v41, v177, v245
	v_bfi_b32 v40, v40, v177, v245
	v_bfi_b32 v39, v39, v177, v245
	v_bfi_b32 v38, v38, v177, v245
	v_bfi_b32 v37, v37, v177, v245
	v_bfi_b32 v36, v36, v177, v245
	v_bfi_b32 v35, v35, v177, v245
	v_bfi_b32 v34, v34, v177, v245
	v_lshrrev_b32_e32 v50, v152, v141
	s_cbranch_vccz .LBB0_1074
	v_and_b32_e32 v192, 64, v240
	v_xor_b32_e32 v213, 32, v240
	v_add_u32_e32 v192, 64, v192
	v_cmp_lt_i32_e32 vcc, v213, v192
	s_nop 1
	v_cndmask_b32_e32 v213, v240, v213, vcc
	v_lshlrev_b32_e32 v213, 2, v213
	ds_bpermute_b32 v213, v213, v212
	v_max_f32_e32 v212, v212, v212
	s_waitcnt lgkmcnt(0)
	v_max_f32_e32 v213, v213, v213
	v_max_f32_e32 v212, v212, v213
	v_log_f32_e32 v213, v212
	v_cmp_lt_f32_e32 vcc, s61, v212
	v_floor_f32_e32 v213, v213
	s_nop 0
	v_cndmask_b32_e32 v212, 0, v213, vcc
	v_exp_f32_e64 v213, -v212
	s_and_saveexec_b64 s[18:19], s[12:13]
	ds_write_b32 v115, v213 offset:32768
	s_or_b64 exec, exec, s[18:19]
	s_waitcnt lgkmcnt(0)
	v_add_f32_e32 v113, v113, v212
	v_mul_f32_e32 v119, v119, v213
	ds_read_b128 v[192:195], v111 offset:32768
	ds_read_b128 v[196:199], v111 offset:32800
	ds_read_b128 v[200:203], v111 offset:32832
	ds_read_b128 v[204:207], v111 offset:32864
	v_xor_b32_e32 v177, 0x80000000, v113
	v_sub_f32_e32 v34, v34, v212
	v_sub_f32_e32 v35, v35, v212
	v_sub_f32_e32 v36, v36, v212
	v_sub_f32_e32 v37, v37, v212
	v_sub_f32_e32 v38, v38, v212
	v_sub_f32_e32 v39, v39, v212
	v_sub_f32_e32 v40, v40, v212
	v_sub_f32_e32 v41, v41, v212
	v_sub_f32_e32 v42, v42, v212
	v_sub_f32_e32 v43, v43, v212
	v_sub_f32_e32 v44, v44, v212
	v_sub_f32_e32 v45, v45, v212
	v_sub_f32_e32 v46, v46, v212
	v_sub_f32_e32 v47, v47, v212
	v_sub_f32_e32 v48, v48, v212
	v_sub_f32_e32 v49, v49, v212
	s_waitcnt lgkmcnt(3)
	v_pk_mul_f32 v[4:5], v[4:5], v[194:195]
	s_waitcnt lgkmcnt(2)
	v_pk_mul_f32 v[8:9], v[8:9], v[198:199]
	s_waitcnt lgkmcnt(1)
	v_pk_mul_f32 v[12:13], v[12:13], v[202:203]
	s_waitcnt lgkmcnt(0)
	v_pk_mul_f32 v[16:17], v[16:17], v[206:207]
	v_pk_mul_f32 v[14:15], v[14:15], v[204:205]
	v_pk_mul_f32 v[10:11], v[10:11], v[200:201]
	v_pk_mul_f32 v[6:7], v[6:7], v[196:197]
	v_pk_mul_f32 v[2:3], v[2:3], v[192:193]
	v_pk_mul_f32 v[32:33], v[32:33], v[206:207]
	v_pk_mul_f32 v[28:29], v[28:29], v[202:203]
	v_pk_mul_f32 v[24:25], v[24:25], v[198:199]
	v_pk_mul_f32 v[20:21], v[20:21], v[194:195]
	v_pk_mul_f32 v[30:31], v[30:31], v[204:205]
	v_pk_mul_f32 v[26:27], v[26:27], v[200:201]
	v_pk_mul_f32 v[22:23], v[22:23], v[196:197]
	v_pk_mul_f32 v[18:19], v[18:19], v[192:193]

; #define LAS __attribute__((address_space(3)))
; __device__ __forceinline__ void attn_unit(const AttArgs& a, int b, int h, int qb, LAS unsigned char* shm, int tid) {
;     ...
;       for (int par = 0; par < 2; ++par) { const int t = t2 + par;
;         LAS unsigned char* Kb = shm + AT_KV + par * 16384; LAS unsigned char* Vb = Kb + 8192; const u64 mw = mwr[par];
;         if (t + 2 < NT) { kr[par] = *(const u32x4_t*)(ksrc + (size_t)(t + 2) * 64 * 256); vr[par] = *(const u32x4_t*)(vsrc + (size_t)(t + 2) * 64 * 256); mwr[par] = mrow[(size_t)(t + 2) * SEQ]; }
;         f32x16 p0, p1;
;         { const unsigned nm0 = ~((unsigned)mw >> (4 * hi)), nm1 = ~((unsigned)(mw >> 32) >> (4 * hi)), nb = __float_as_uint(-m_run);
; #pragma unroll
;           for (int r = 0; r < 16; ++r) { const int bit = (r & 3) + 8 * (r >> 2); const unsigned t0 = (unsigned)__builtin_amdgcn_sbfe((int)nm0, bit, 1), t1 = (unsigned)__builtin_amdgcn_sbfe((int)nm1, bit, 1);
;               p0[r] = __uint_as_float((t0 & 0xff800000u) | (~t0 & nb)); p1[r] = __uint_as_float((t1 & 0xff800000u) | (~t1 & nb)); } }
;         { LAS unsigned char* kb = Kb + hi * 1024 + r32 * 16;
; #pragma unroll
;           for (int d0 = 0; d0 < 4; ++d0) { const bf16x8 k0 = *(const LAS bf16x8*)(kb + d0 * 2048), k1 = *(const LAS bf16x8*)(kb + d0 * 2048 + 512);
;               p0 = __builtin_amdgcn_mfma_f32_32x32x16_bf16(k0, qr[d0], p0, 0, 0, 0); p1 = __builtin_amdgcn_mfma_f32_32x32x16_bf16(k1, qr[d0], p1, 0, 0, 0); } }
;         if (t == 0) {
;             float rm = __builtin_amdgcn_fmed3f(p0[0], p1[0], BIGF);
; #pragma unroll
;             for (int r = 1; r < 16; ++r) rm = __builtin_amdgcn_fmed3f(rm, __builtin_amdgcn_fmed3f(p0[r], p1[r], BIGF), BIGF);
;             const float rmf = __builtin_amdgcn_fmed3f(rm, __shfl_xor(rm, 32), BIGF); const float dl = (rmf == -INFINITY) ? 0.f : rmf;
;             m_run += dl;
; #pragma unroll
;             for (int r = 0; r < 16; ++r) { p0[r] -= dl; p1[r] -= dl; } }
;         float rs;
;         { typedef float f32x2_t __attribute__((ext_vector_type(2))); f32x2_t rs2 = {0.f, 0.f};
; #pragma unroll
;           for (int r = 0; r < 16; ++r) { p0[r] = __builtin_amdgcn_exp2f(p0[r]); p1[r] = __builtin_amdgcn_exp2f(p1[r]); rs2 += (f32x2_t){p0[r], p1[r]}; }
;           rs = rs2[0] + rs2[1]; l_run += rs; }
.LBB0_1076:
	s_cmp_ge_u32 s25, s26
	s_waitcnt vmcnt(2)
	v_mov_b64_e32 v[148:149], v[140:141]
	s_waitcnt lgkmcnt(0)
	s_barrier
	ds_read_b128 v[178:181], v176 offset:16384
	ds_read_b128 v[182:185], v176 offset:18432
	ds_read_b128 v[186:189], v176 offset:20480
	ds_read_b128 v[192:195], v176 offset:22528
	ds_read_b128 v[196:199], v176 offset:16896
	ds_read_b128 v[200:203], v176 offset:18944
	ds_read_b128 v[204:207], v176 offset:20992
	ds_read_b128 v[208:211], v176 offset:23040
	s_cbranch_scc1 .LBB0_1078
	v_add_co_u32_e32 v212, vcc, 0x1df18000, v146
	s_nop 1
	v_addc_co_u32_e32 v213, vcc, 0, v147, vcc
	global_load_dwordx4 v[90:93], v[212:213], off
	v_add_co_u32_e32 v148, vcc, 0x1e718000, v144
	s_nop 1
	v_addc_co_u32_e32 v149, vcc, 0, v145, vcc
	global_load_dwordx4 v[94:97], v[148:149], off
	v_add_co_u32_e32 v212, vcc, 0x1c718000, v142
	s_nop 1
	v_addc_co_u32_e32 v213, vcc, 0, v143, vcc
	global_load_dwordx2 v[148:149], v[212:213], off
.LBB0_1078:
	v_bfe_i32 v65, v50, 27, 1
	v_bfe_i32 v64, v50, 26, 1
	v_bfe_i32 v63, v50, 25, 1
	v_bfe_i32 v62, v50, 24, 1
	v_bfe_i32 v61, v50, 19, 1
	v_bfe_i32 v60, v50, 18, 1
	v_bfe_i32 v59, v50, 17, 1
	v_bfe_i32 v58, v50, 16, 1
	s_waitcnt lgkmcnt(7)
	v_mfma_f32_32x32x16_bf16 v[34:49], v[178:181], v[66:69], v[34:49]
	v_bfe_i32 v57, v50, 11, 1
	v_bfe_i32 v56, v50, 10, 1
	v_bfe_i32 v55, v50, 9, 1
	v_bfe_i32 v54, v50, 8, 1
	v_bfe_i32 v53, v50, 3, 1
	v_bfe_i32 v52, v50, 2, 1
	v_bfe_i32 v51, v50, 1, 1
	v_bfe_i32 v50, v50, 0, 1
	s_waitcnt lgkmcnt(6)
	v_mfma_f32_32x32x16_bf16 v[34:49], v[182:185], v[70:73], v[34:49]
	v_bfi_b32 v65, v65, v177, v245
	v_bfi_b32 v64, v64, v177, v245
	v_bfi_b32 v63, v63, v177, v245
	v_bfi_b32 v62, v62, v177, v245
	v_bfi_b32 v61, v61, v177, v245
	v_bfi_b32 v60, v60, v177, v245
	v_bfi_b32 v59, v59, v177, v245
	v_bfi_b32 v58, v58, v177, v245
	s_waitcnt lgkmcnt(5)
	v_mfma_f32_32x32x16_bf16 v[34:49], v[186:189], v[74:77], v[34:49]
	v_bfi_b32 v57, v57, v177, v245
	v_bfi_b32 v56, v56, v177, v245
	v_bfi_b32 v55, v55, v177, v245
	v_bfi_b32 v54, v54, v177, v245
	v_bfi_b32 v53, v53, v177, v245
	v_bfi_b32 v52, v52, v177, v245
	v_bfi_b32 v51, v51, v177, v245
	v_bfi_b32 v50, v50, v177, v245
	s_waitcnt lgkmcnt(4)
	v_mfma_f32_32x32x16_bf16 v[34:49], v[192:195], v[78:81], v[34:49]
	ds_read_b64_tr_b16 v[178:179],v154 offset:0
	ds_read_b64_tr_b16 v[180:181],v154 offset:512
	ds_read_b64_tr_b16 v[182:183],v154 offset:4096
	ds_read_b64_tr_b16 v[184:185],v154 offset:4608
	ds_read_b64_tr_b16 v[186:187],v154 offset:1024
	ds_read_b64_tr_b16 v[188:189],v154 offset:1536
	ds_read_b64_tr_b16 v[192:193],v154 offset:5120
	ds_read_b64_tr_b16 v[194:195],v154 offset:5632
	s_waitcnt lgkmcnt(11)
	v_mfma_f32_32x32x16_bf16 v[50:65], v[196:199], v[66:69], v[50:65]
	s_nop 3
	v_exp_f32_e32 v34, v34
	v_exp_f32_e32 v35, v35
	v_exp_f32_e32 v36, v36
	v_exp_f32_e32 v37, v37
	s_waitcnt lgkmcnt(10)
	v_mfma_f32_32x32x16_bf16 v[50:65], v[200:203], v[70:73], v[50:65]
	v_exp_f32_e32 v38, v38
	v_exp_f32_e32 v39, v39
	v_exp_f32_e32 v40, v40
	v_exp_f32_e32 v41, v41
	s_waitcnt lgkmcnt(9)
	v_mfma_f32_32x32x16_bf16 v[50:65], v[204:207], v[74:77], v[50:65]
	v_exp_f32_e32 v42, v42
	v_exp_f32_e32 v43, v43
	v_exp_f32_e32 v44, v44
	v_exp_f32_e32 v45, v45
	s_waitcnt lgkmcnt(8)
	v_mfma_f32_32x32x16_bf16 v[50:65], v[208:211], v[78:81], v[50:65]
	v_exp_f32_e32 v46, v46
	v_exp_f32_e32 v47, v47
	v_exp_f32_e32 v48, v48
	v_exp_f32_e32 v49, v49
	v_cvt_pk_bf16_f32 v196, v34, v35
	v_pk_add_f32 v[212:213], v[34:35], v[36:37]
	v_cvt_pk_bf16_f32 v197, v36, v37
	v_pk_add_f32 v[212:213], v[38:39], v[212:213]
	v_cvt_pk_bf16_f32 v198, v38, v39
	v_pk_add_f32 v[212:213], v[40:41], v[212:213]
	v_cvt_pk_bf16_f32 v199, v40, v41
	v_pk_add_f32 v[212:213], v[42:43], v[212:213]
	v_cvt_pk_bf16_f32 v200, v42, v43
	v_pk_add_f32 v[212:213], v[44:45], v[212:213]
	v_cvt_pk_bf16_f32 v201, v44, v45
	v_pk_add_f32 v[212:213], v[46:47], v[212:213]
	v_cvt_pk_bf16_f32 v202, v46, v47
	v_pk_add_f32 v[212:213], v[48:49], v[212:213]
	v_cvt_pk_bf16_f32 v203, v48, v49
	s_waitcnt lgkmcnt(0)
; __device__ __forceinline__ void attn_unit(const AttArgs& a, int b, int h, int qb, LAS unsigned char* shm, int tid) {
;     ...
;           for (int r = 0; r < 16; ++r) { p0[r] = __builtin_amdgcn_exp2f(p0[r]); p1[r] = __builtin_amdgcn_exp2f(p1[r]); rs2 += (f32x2_t){p0[r], p1[r]}; }
;           rs = rs2[0] + rs2[1]; l_run += rs; }
;         const bool regrow = __any(rs > 1.0995e12f);
;         u32x4_t pw0, pw1, pw2, pw3;
;         pw0 = (u32x4_t){cvtpk(p0[0], p0[1]), cvtpk(p0[2], p0[3]), cvtpk(p0[4], p0[5]), cvtpk(p0[6], p0[7])}; pw1 = (u32x4_t){cvtpk(p0[8], p0[9]), cvtpk(p0[10], p0[11]), cvtpk(p0[12], p0[13]), cvtpk(p0[14], p0[15])};
;         pw2 = (u32x4_t){cvtpk(p1[0], p1[1]), cvtpk(p1[2], p1[3]), cvtpk(p1[4], p1[5]), cvtpk(p1[6], p1[7])}; pw3 = (u32x4_t){cvtpk(p1[8], p1[9]), cvtpk(p1[10], p1[11]), cvtpk(p1[12], p1[13]), cvtpk(p1[14], p1[15])};
;         { const unsigned vb = (unsigned)(uintptr_t)Vb + ((lane >> 4) & 1) * 32 + (lane & 3) * 8 + (4 * hi + ((lane & 15) >> 2)) * 64;
; #pragma unroll
;           for (int d0 = 0; d0 < 2; ++d0) { s16x4 lo[4], hh[4];
; #pragma unroll
;               for (int ks = 0; ks < 4; ++ks) {
;                   asm volatile("ds_read_b64_tr_b16 %0,%1 offset:%c2" : "=&v"(lo[ks]) : "v"(vb), "i"(d0 * 4096 + ks * 1024) : "memory");
;                   asm volatile("ds_read_b64_tr_b16 %0,%1 offset:%c2" : "=&v"(hh[ks]) : "v"(vb), "i"(d0 * 4096 + ks * 1024 + 512) : "memory"); }
;               asm volatile("s_waitcnt lgkmcnt(0)" ::: "memory"); __builtin_amdgcn_sched_barrier(0);
;     ...
;               o[d0] = __builtin_amdgcn_mfma_f32_32x32x16_bf16(__builtin_bit_cast(bf16x8, pw0), DSA_PK(0), o[d0], 0, 0, 0);
;               o[d0] = __builtin_amdgcn_mfma_f32_32x32x16_bf16(__builtin_bit_cast(bf16x8, pw1), DSA_PK(1), o[d0], 0, 0, 0);
;               o[d0] = __builtin_amdgcn_mfma_f32_32x32x16_bf16(__builtin_bit_cast(bf16x8, pw2), DSA_PK(2), o[d0], 0, 0, 0);
;               o[d0] = __builtin_amdgcn_mfma_f32_32x32x16_bf16(__builtin_bit_cast(bf16x8, pw3), DSA_PK(3), o[d0], 0, 0, 0);
;     ...
;           } }
;         if (regrow) { const float rsf = __builtin_amdgcn_fmed3f(rs, __shfl_xor(rs, 32), INFINITY); const float dl = rsf > 1.0995e12f ? floorf(__log2f(rsf)) : 0.f;
;             m_run += dl; const float alpha = __builtin_amdgcn_exp2f(-dl); l_run *= alpha;
;             if (hi == 0) wsf[r32] = alpha; asm volatile("s_waitcnt lgkmcnt(0)" ::: "memory");
	v_mfma_f32_32x32x16_bf16 v[2:17], v[196:199], v[178:181], v[2:17]
	ds_read_b64_tr_b16 v[178:179],v154 offset:2048
	ds_read_b64_tr_b16 v[180:181],v154 offset:2560
	v_exp_f32_e32 v50, v50
	v_exp_f32_e32 v51, v51
	v_exp_f32_e32 v52, v52
	v_exp_f32_e32 v53, v53
	v_mfma_f32_32x32x16_bf16 v[18:33], v[196:199], v[182:185], v[18:33]
	ds_read_b64_tr_b16 v[182:183],v154 offset:6144
	ds_read_b64_tr_b16 v[184:185],v154 offset:6656
	v_exp_f32_e32 v54, v54
	v_exp_f32_e32 v55, v55
	v_exp_f32_e32 v56, v56
	v_exp_f32_e32 v57, v57
	v_mfma_f32_32x32x16_bf16 v[2:17], v[200:203], v[186:189], v[2:17]
	ds_read_b64_tr_b16 v[186:187],v154 offset:3072
	ds_read_b64_tr_b16 v[188:189],v154 offset:3584
	v_exp_f32_e32 v58, v58
	v_exp_f32_e32 v59, v59
	v_exp_f32_e32 v60, v60
	v_exp_f32_e32 v61, v61
	v_mfma_f32_32x32x16_bf16 v[18:33], v[200:203], v[192:195], v[18:33]
	ds_read_b64_tr_b16 v[192:193],v154 offset:7168
	ds_read_b64_tr_b16 v[194:195],v154 offset:7680
	v_exp_f32_e32 v62, v62
	v_exp_f32_e32 v63, v63
	v_exp_f32_e32 v64, v64
	v_exp_f32_e32 v65, v65
	v_cvt_pk_bf16_f32 v204, v50, v51
	v_cvt_pk_bf16_f32 v205, v52, v53
	v_cvt_pk_bf16_f32 v206, v54, v55
	v_cvt_pk_bf16_f32 v207, v56, v57
	v_cvt_pk_bf16_f32 v208, v58, v59
	v_cvt_pk_bf16_f32 v209, v60, v61
	v_cvt_pk_bf16_f32 v210, v62, v63
	v_cvt_pk_bf16_f32 v211, v64, v65
	v_pk_add_f32 v[212:213], v[50:51], v[212:213]
	v_pk_add_f32 v[212:213], v[52:53], v[212:213]
	v_pk_add_f32 v[212:213], v[54:55], v[212:213]
	v_pk_add_f32 v[212:213], v[56:57], v[212:213]
	v_pk_add_f32 v[212:213], v[58:59], v[212:213]
	v_pk_add_f32 v[212:213], v[60:61], v[212:213]
	v_pk_add_f32 v[212:213], v[62:63], v[212:213]
	v_pk_add_f32 v[212:213], v[64:65], v[212:213]
	v_add_f32_e32 v212, v212, v213
	v_cmp_lt_f32_e32 vcc, s61, v212
	v_add_f32_e32 v119, v119, v212
	s_waitcnt lgkmcnt(6)
	v_mfma_f32_32x32x16_bf16 v[2:17], v[204:207], v[178:181], v[2:17]
	v_lshrrev_b32_e32 v34, v152, v138
	v_xor_b32_e32 v177, 0x80000000, v113
	v_bfe_i32 v49, v34, 27, 1
	v_bfe_i32 v48, v34, 26, 1
	v_bfe_i32 v47, v34, 25, 1
	v_bfe_i32 v46, v34, 24, 1
	v_bfe_i32 v45, v34, 19, 1
	v_bfe_i32 v44, v34, 18, 1
	v_bfe_i32 v43, v34, 17, 1
	s_waitcnt lgkmcnt(4)
	v_mfma_f32_32x32x16_bf16 v[18:33], v[204:207], v[182:185], v[18:33]
	v_bfe_i32 v42, v34, 16, 1
	v_bfe_i32 v41, v34, 11, 1
	v_bfe_i32 v40, v34, 10, 1
	v_bfe_i32 v39, v34, 9, 1
	v_bfe_i32 v38, v34, 8, 1
	v_bfe_i32 v37, v34, 3, 1
	v_bfe_i32 v36, v34, 2, 1
	v_bfe_i32 v35, v34, 1, 1
	v_bfe_i32 v34, v34, 0, 1
	s_waitcnt lgkmcnt(2)
	v_mfma_f32_32x32x16_bf16 v[2:17], v[208:211], v[186:189], v[2:17]
	v_bfi_b32 v49, v49, v177, v245
	v_bfi_b32 v48, v48, v177, v245
	v_bfi_b32 v47, v47, v177, v245
	v_bfi_b32 v46, v46, v177, v245
	v_bfi_b32 v45, v45, v177, v245
	v_bfi_b32 v44, v44, v177, v245
	v_bfi_b32 v43, v43, v177, v245
	v_bfi_b32 v42, v42, v177, v245
	v_bfi_b32 v41, v41, v177, v245
	s_waitcnt lgkmcnt(0)
	v_mfma_f32_32x32x16_bf16 v[18:33], v[208:211], v[192:195], v[18:33]
	v_bfi_b32 v40, v40, v177, v245
	v_bfi_b32 v39, v39, v177, v245
	v_bfi_b32 v38, v38, v177, v245
	v_bfi_b32 v37, v37, v177, v245
	v_bfi_b32 v36, v36, v177, v245
	v_bfi_b32 v35, v35, v177, v245
	v_bfi_b32 v34, v34, v177, v245
	v_lshrrev_b32_e32 v50, v152, v139
	s_cbranch_vccz .LBB0_1082
	v_and_b32_e32 v192, 64, v240
	v_xor_b32_e32 v213, 32, v240
	v_add_u32_e32 v192, 64, v192
	v_cmp_lt_i32_e32 vcc, v213, v192
	s_nop 1
	v_cndmask_b32_e32 v213, v240, v213, vcc
	v_lshlrev_b32_e32 v213, 2, v213
	ds_bpermute_b32 v213, v213, v212
	v_max_f32_e32 v212, v212, v212
	s_waitcnt lgkmcnt(0)
	v_max_f32_e32 v213, v213, v213
	v_max_f32_e32 v212, v212, v213
	v_log_f32_e32 v213, v212
	v_cmp_lt_f32_e32 vcc, s61, v212
	v_floor_f32_e32 v213, v213
	s_nop 0
	v_cndmask_b32_e32 v212, 0, v213, vcc
	v_exp_f32_e64 v213, -v212
	s_and_saveexec_b64 s[18:19], s[12:13]
	ds_write_b32 v115, v213 offset:32768
	s_or_b64 exec, exec, s[18:19]
	s_waitcnt lgkmcnt(0)
	v_add_f32_e32 v113, v113, v212
	v_mul_f32_e32 v119, v119, v213
	ds_read_b128 v[192:195], v111 offset:32768
	ds_read_b128 v[196:199], v111 offset:32800
	ds_read_b128 v[200:203], v111 offset:32832
	ds_read_b128 v[204:207], v111 offset:32864
	v_xor_b32_e32 v177, 0x80000000, v113
	v_sub_f32_e32 v34, v34, v212
	v_sub_f32_e32 v35, v35, v212
	v_sub_f32_e32 v36, v36, v212
	v_sub_f32_e32 v37, v37, v212
	v_sub_f32_e32 v38, v38, v212
	v_sub_f32_e32 v39, v39, v212
	v_sub_f32_e32 v40, v40, v212
	v_sub_f32_e32 v41, v41, v212
	v_sub_f32_e32 v42, v42, v212
	v_sub_f32_e32 v43, v43, v212
	v_sub_f32_e32 v44, v44, v212
	v_sub_f32_e32 v45, v45, v212
	v_sub_f32_e32 v46, v46, v212
	v_sub_f32_e32 v47, v47, v212
	v_sub_f32_e32 v48, v48, v212
	v_sub_f32_e32 v49, v49, v212
	s_waitcnt lgkmcnt(3)
	v_pk_mul_f32 v[4:5], v[4:5], v[194:195]
	s_waitcnt lgkmcnt(2)
	v_pk_mul_f32 v[8:9], v[8:9], v[198:199]
	s_waitcnt lgkmcnt(1)
	v_pk_mul_f32 v[12:13], v[12:13], v[202:203]
	s_waitcnt lgkmcnt(0)
	v_pk_mul_f32 v[16:17], v[16:17], v[206:207]
	v_pk_mul_f32 v[14:15], v[14:15], v[204:205]
	v_pk_mul_f32 v[10:11], v[10:11], v[200:201]
	v_pk_mul_f32 v[6:7], v[6:7], v[196:197]
	v_pk_mul_f32 v[2:3], v[2:3], v[192:193]
	v_pk_mul_f32 v[32:33], v[32:33], v[206:207]
	v_pk_mul_f32 v[28:29], v[28:29], v[202:203]
	v_pk_mul_f32 v[24:25], v[24:25], v[198:199]
	v_pk_mul_f32 v[20:21], v[20:21], v[194:195]
	v_pk_mul_f32 v[30:31], v[30:31], v[204:205]
	v_pk_mul_f32 v[26:27], v[26:27], v[200:201]
	v_pk_mul_f32 v[22:23], v[22:23], v[196:197]
	v_pk_mul_f32 v[18:19], v[18:19], v[192:193]

; #define LAS __attribute__((address_space(3)))
; __device__ __forceinline__ void attn_unit(const AttArgs& a, int b, int h, int qb, LAS unsigned char* shm, int tid) {
;     ...
;         if (t == 0) {
;             float rm = __builtin_amdgcn_fmed3f(p0[0], p1[0], BIGF);
; #pragma unroll
;             for (int r = 1; r < 16; ++r) rm = __builtin_amdgcn_fmed3f(rm, __builtin_amdgcn_fmed3f(p0[r], p1[r], BIGF), BIGF);
;             const float rmf = __builtin_amdgcn_fmed3f(rm, __shfl_xor(rm, 32), BIGF); const float dl = (rmf == -INFINITY) ? 0.f : rmf;
;             m_run += dl;
; #pragma unroll
;             for (int r = 0; r < 16; ++r) { p0[r] -= dl; p1[r] -= dl; } }
;         float rs;
;         { typedef float f32x2_t __attribute__((ext_vector_type(2))); f32x2_t rs2 = {0.f, 0.f};
; #pragma unroll
;           for (int r = 0; r < 16; ++r) { p0[r] = __builtin_amdgcn_exp2f(p0[r]); p1[r] = __builtin_amdgcn_exp2f(p1[r]); rs2 += (f32x2_t){p0[r], p1[r]}; }
;     ...
;         if (t + 1 < NT) { LAS unsigned char* Kn = shm + AT_KV + (par ^ 1) * 16384; *(LAS u32x4_t*)(Kn + wave * 1024 + lane * 16) = kr[par ^ 1]; *(LAS u32x4_t*)(Kn + 8192 + wave * 1024 + lane * 16) = vr[par ^ 1]; }
;         __syncthreads();
;       }
.LBB0_1084:
	s_add_u32 s14, s14, 0x10000
	s_addc_u32 s15, s15, 0
	s_add_i32 s25, s25, 2
	s_cmp_ge_u32 s27, s26
	s_waitcnt lgkmcnt(0)
	s_barrier
	s_cbranch_scc1 .LBB0_1086
	s_waitcnt vmcnt(0)
	v_mov_b64_e32 v[140:141], v[148:149]
	s_branch .LBB0_1066
.Latt_t0:
	s_waitcnt lgkmcnt(11)
	v_mfma_f32_32x32x16_bf16 v[50:65], v[196:199], v[66:69], v[50:65]
	s_waitcnt lgkmcnt(10)
	v_mfma_f32_32x32x16_bf16 v[50:65], v[200:203], v[70:73], v[50:65]
	s_waitcnt lgkmcnt(9)
	v_mfma_f32_32x32x16_bf16 v[50:65], v[204:207], v[74:77], v[50:65]
	s_waitcnt lgkmcnt(8)
	v_mfma_f32_32x32x16_bf16 v[50:65], v[208:211], v[78:81], v[50:65]
	s_nop 10
	v_med3_f32 v148, v34, v50, s89
	v_med3_f32 v149, v35, v51, s89
	v_med3_f32 v148, v148, v149, s89
	v_med3_f32 v149, v36, v52, s89
	v_med3_f32 v148, v148, v149, s89
	v_med3_f32 v149, v37, v53, s89
	v_med3_f32 v148, v148, v149, s89
	v_med3_f32 v149, v38, v54, s89
	v_med3_f32 v148, v148, v149, s89
	v_med3_f32 v149, v39, v55, s89
	v_med3_f32 v148, v148, v149, s89
	v_med3_f32 v149, v40, v56, s89
	v_med3_f32 v148, v148, v149, s89
	v_med3_f32 v149, v41, v57, s89
	v_med3_f32 v148, v148, v149, s89
	v_med3_f32 v149, v42, v58, s89
	v_med3_f32 v148, v148, v149, s89
	v_med3_f32 v149, v43, v59, s89
	v_med3_f32 v148, v148, v149, s89
	v_med3_f32 v149, v44, v60, s89
	v_med3_f32 v148, v148, v149, s89
	v_med3_f32 v149, v45, v61, s89
	v_med3_f32 v148, v148, v149, s89
	v_med3_f32 v149, v46, v62, s89
	v_med3_f32 v148, v148, v149, s89
	v_med3_f32 v149, v47, v63, s89
	v_med3_f32 v148, v148, v149, s89
	v_med3_f32 v149, v48, v64, s89
	v_med3_f32 v148, v148, v149, s89
	v_med3_f32 v149, v49, v65, s89
	v_and_b32_e32 v177, 64, v240
	v_med3_f32 v148, v148, v149, s89
	v_xor_b32_e32 v149, 32, v240
	v_add_u32_e32 v177, 64, v177
	v_cmp_lt_i32_e32 vcc, v149, v177
	s_nop 1
	v_cndmask_b32_e32 v149, v240, v149, vcc
	v_lshlrev_b32_e32 v149, 2, v149
	ds_bpermute_b32 v149, v149, v148
	s_waitcnt lgkmcnt(0)
	v_med3_f32 v148, v148, v149, s89
	v_cmp_neq_f32_e32 vcc, s90, v148
	s_nop 1
	v_cndmask_b32_e32 v148, 0, v148, vcc
	v_sub_f32_e32 v49, v49, v148
	v_sub_f32_e32 v48, v48, v148
	v_sub_f32_e32 v47, v47, v148
	v_sub_f32_e32 v46, v46, v148
	v_sub_f32_e32 v45, v45, v148
	v_sub_f32_e32 v44, v44, v148
	v_sub_f32_e32 v43, v43, v148
	v_sub_f32_e32 v42, v42, v148
	v_sub_f32_e32 v41, v41, v148
	v_sub_f32_e32 v40, v40, v148
	v_sub_f32_e32 v39, v39, v148
	v_sub_f32_e32 v38, v38, v148
	v_sub_f32_e32 v37, v37, v148
	v_sub_f32_e32 v36, v36, v148
	v_sub_f32_e32 v35, v35, v148
	v_sub_f32_e32 v34, v34, v148
	v_sub_f32_e32 v65, v65, v148
	v_sub_f32_e32 v64, v64, v148
	v_sub_f32_e32 v63, v63, v148
	v_sub_f32_e32 v62, v62, v148
	v_sub_f32_e32 v61, v61, v148
	v_sub_f32_e32 v60, v60, v148
	v_sub_f32_e32 v59, v59, v148
	v_sub_f32_e32 v58, v58, v148
	v_sub_f32_e32 v57, v57, v148
	v_sub_f32_e32 v56, v56, v148
	v_sub_f32_e32 v55, v55, v148
	v_sub_f32_e32 v54, v54, v148
	v_sub_f32_e32 v53, v53, v148
	v_sub_f32_e32 v52, v52, v148
	v_sub_f32_e32 v51, v51, v148
	v_sub_f32_e32 v50, v50, v148
	v_add_f32_e32 v113, v113, v148
	v_exp_f32_e32 v34, v34
	v_exp_f32_e32 v35, v35
	v_exp_f32_e32 v36, v36
	v_exp_f32_e32 v37, v37
	v_exp_f32_e32 v38, v38
	v_exp_f32_e32 v39, v39
	v_exp_f32_e32 v40, v40
	v_exp_f32_e32 v41, v41
	v_exp_f32_e32 v42, v42
	v_exp_f32_e32 v43, v43
	v_exp_f32_e32 v44, v44
	v_exp_f32_e32 v45, v45
	v_exp_f32_e32 v46, v46
	v_exp_f32_e32 v47, v47
	v_exp_f32_e32 v48, v48
	v_exp_f32_e32 v49, v49
	s_branch .Latt_j0

; #define LAS __attribute__((address_space(3)))
; __device__ __forceinline__ void sdsa2_phase(const Grp& g, LAS unsigned char* shm, int G, int tid) {
;     ...
;         { const int n = tid >> 7, kg = (tid >> 4) & 7, d4 = tid & 15; const LAS float* p0 = P + (2 * n) * 256; const LAS float* p1 = p0 + 256; float4 a0 = make_float4(0.f, 0.f, 0.f, 0.f), a1 = a0;
; #pragma unroll 16
;           for (int jj = 0; jj < 32; ++jj) { const int j = kg * 32 + jj, jc = j < ns ? j : ns - 1; const int sr = sel[jc];
;               const float* vr = (sr & 0x40000000) ? g.AV + ((size_t)db * g.L + (sr & 0xffff)) * KVW : g.cache_v + (size_t)sr * KVW;
;               const float4 vv = *(const float4*)(vr + n * 64 + 4 * d4); const float w0 = p0[j], w1 = p1[j];
;               a0.x = fmaf(w0, vv.x, a0.x); a0.y = fmaf(w0, vv.y, a0.y); a0.z = fmaf(w0, vv.z, a0.z); a0.w = fmaf(w0, vv.w, a0.w); a1.x = fmaf(w1, vv.x, a1.x); a1.y = fmaf(w1, vv.y, a1.y); a1.z = fmaf(w1, vv.z, a1.z); a1.w = fmaf(w1, vv.w, a1.w); }
.LBB0_1221:
	v_add_u32_e32 v55, s2, v143
	v_mov_b32_e32 v51, s63
	v_mov_b32_e32 v52, s11
	v_mov_b32_e32 v53, s62
	v_mov_b32_e32 v54, s10
	v_mov_b32_e32 v172, v55
	v_min_i32_e32 v172, v172, v154
	v_lshl_add_u32 v172, v172, 2, 0
	ds_read_b32 v42, v172 offset:33024
	v_add_u32_e32 v172, 1, v55
	v_min_i32_e32 v172, v172, v154
	v_lshl_add_u32 v172, v172, 2, 0
	ds_read_b32 v43, v172 offset:33024
	v_add_u32_e32 v172, 2, v55
	v_min_i32_e32 v172, v172, v154
	v_lshl_add_u32 v172, v172, 2, 0
	ds_read_b32 v44, v172 offset:33024
	v_add_u32_e32 v172, 3, v55
	v_min_i32_e32 v172, v172, v154
	v_lshl_add_u32 v172, v172, 2, 0
	ds_read_b32 v45, v172 offset:33024
	v_add_u32_e32 v172, 4, v55
	v_min_i32_e32 v172, v172, v154
	v_lshl_add_u32 v172, v172, 2, 0
	ds_read_b32 v46, v172 offset:33024
	v_add_u32_e32 v172, 5, v55
	v_min_i32_e32 v172, v172, v154
	v_lshl_add_u32 v172, v172, 2, 0
	ds_read_b32 v47, v172 offset:33024
	v_add_u32_e32 v172, 6, v55
	v_min_i32_e32 v172, v172, v154
	v_lshl_add_u32 v172, v172, 2, 0
	ds_read_b32 v48, v172 offset:33024
	v_add_u32_e32 v172, 7, v55
	v_min_i32_e32 v172, v172, v154
	v_lshl_add_u32 v172, v172, 2, 0
	ds_read_b32 v49, v172 offset:33024
	v_add_u32_e32 v172, 8, v55
	v_min_i32_e32 v172, v172, v154
	v_lshl_add_u32 v172, v172, 2, 0
	ds_read_b32 v56, v172 offset:33024
	v_add_u32_e32 v172, 9, v55
	v_min_i32_e32 v172, v172, v154
	v_lshl_add_u32 v172, v172, 2, 0
	ds_read_b32 v57, v172 offset:33024
	v_add_u32_e32 v172, 10, v55
	v_min_i32_e32 v172, v172, v154
	v_lshl_add_u32 v172, v172, 2, 0
	ds_read_b32 v58, v172 offset:33024
	v_add_u32_e32 v172, 11, v55
	v_min_i32_e32 v172, v172, v154
	v_lshl_add_u32 v172, v172, 2, 0
	ds_read_b32 v59, v172 offset:33024
	v_add_u32_e32 v172, 12, v55
	v_min_i32_e32 v172, v172, v154
	v_lshl_add_u32 v172, v172, 2, 0
	ds_read_b32 v60, v172 offset:33024
	v_add_u32_e32 v172, 13, v55
	v_min_i32_e32 v172, v172, v154
	v_lshl_add_u32 v172, v172, 2, 0
	ds_read_b32 v61, v172 offset:33024
	v_add_u32_e32 v172, 14, v55
	v_min_i32_e32 v172, v172, v154
	v_lshl_add_u32 v172, v172, 2, 0
	ds_read_b32 v62, v172 offset:33024
	v_add_u32_e32 v172, 15, v55
	v_min_i32_e32 v172, v172, v154
	v_lshl_add_u32 v172, v172, 2, 0
	ds_read_b32 v63, v172 offset:33024
	s_waitcnt lgkmcnt(0)
	v_and_b32_e32 v172, 2.0, v42
	v_cmp_eq_u32_e32 vcc, 0, v172
	v_and_b32_e32 v172, 0xffff, v42
	v_ashrrev_i32_e32 v175, 31, v42
	v_mov_b32_e32 v173, v215
	v_lshl_add_u64 v[172:173], s[0:1], 0, v[172:173]
	v_cndmask_b32_e32 v173, v173, v175, vcc
	v_cndmask_b32_e32 v172, v172, v42, vcc
	v_cndmask_b32_e32 v175, v51, v52, vcc
	v_cndmask_b32_e32 v174, v53, v54, vcc
	v_lshlrev_b64 v[172:173], 10, v[172:173]
	v_lshl_add_u64 v[172:173], v[174:175], 0, v[172:173]
	v_lshl_add_u64 v[172:173], v[172:173], 0, v[118:119]
	v_lshl_add_u64 v[172:173], v[172:173], 0, v[214:215]
	global_load_dwordx4 v[2:5], v[172:173], off
	v_and_b32_e32 v172, 2.0, v43
	v_cmp_eq_u32_e32 vcc, 0, v172
	v_and_b32_e32 v172, 0xffff, v43
	v_ashrrev_i32_e32 v175, 31, v43
	v_mov_b32_e32 v173, v215
	v_lshl_add_u64 v[172:173], s[0:1], 0, v[172:173]
	v_cndmask_b32_e32 v173, v173, v175, vcc
	v_cndmask_b32_e32 v172, v172, v43, vcc
	v_cndmask_b32_e32 v175, v51, v52, vcc
	v_cndmask_b32_e32 v174, v53, v54, vcc
	v_lshlrev_b64 v[172:173], 10, v[172:173]
	v_lshl_add_u64 v[172:173], v[174:175], 0, v[172:173]
	v_lshl_add_u64 v[172:173], v[172:173], 0, v[118:119]
	v_lshl_add_u64 v[172:173], v[172:173], 0, v[214:215]
	global_load_dwordx4 v[6:9], v[172:173], off
	v_and_b32_e32 v172, 2.0, v44
	v_cmp_eq_u32_e32 vcc, 0, v172
	v_and_b32_e32 v172, 0xffff, v44
	v_ashrrev_i32_e32 v175, 31, v44
	v_mov_b32_e32 v173, v215
	v_lshl_add_u64 v[172:173], s[0:1], 0, v[172:173]
	v_cndmask_b32_e32 v173, v173, v175, vcc
	v_cndmask_b32_e32 v172, v172, v44, vcc
	v_cndmask_b32_e32 v175, v51, v52, vcc
	v_cndmask_b32_e32 v174, v53, v54, vcc
	v_lshlrev_b64 v[172:173], 10, v[172:173]
	v_lshl_add_u64 v[172:173], v[174:175], 0, v[172:173]
	v_lshl_add_u64 v[172:173], v[172:173], 0, v[118:119]
	v_lshl_add_u64 v[172:173], v[172:173], 0, v[214:215]
	global_load_dwordx4 v[10:13], v[172:173], off
	v_and_b32_e32 v172, 2.0, v45
	v_cmp_eq_u32_e32 vcc, 0, v172
	v_and_b32_e32 v172, 0xffff, v45
	v_ashrrev_i32_e32 v175, 31, v45
	v_mov_b32_e32 v173, v215
	v_lshl_add_u64 v[172:173], s[0:1], 0, v[172:173]
	v_cndmask_b32_e32 v173, v173, v175, vcc
	v_cndmask_b32_e32 v172, v172, v45, vcc
	v_cndmask_b32_e32 v175, v51, v52, vcc
	v_cndmask_b32_e32 v174, v53, v54, vcc
	v_lshlrev_b64 v[172:173], 10, v[172:173]
	v_lshl_add_u64 v[172:173], v[174:175], 0, v[172:173]
	v_lshl_add_u64 v[172:173], v[172:173], 0, v[118:119]
	v_lshl_add_u64 v[172:173], v[172:173], 0, v[214:215]
	global_load_dwordx4 v[14:17], v[172:173], off
	v_and_b32_e32 v172, 2.0, v46
	v_cmp_eq_u32_e32 vcc, 0, v172
	v_and_b32_e32 v172, 0xffff, v46
	v_ashrrev_i32_e32 v175, 31, v46
	v_mov_b32_e32 v173, v215
	v_lshl_add_u64 v[172:173], s[0:1], 0, v[172:173]
	v_cndmask_b32_e32 v173, v173, v175, vcc
	v_cndmask_b32_e32 v172, v172, v46, vcc
	v_cndmask_b32_e32 v175, v51, v52, vcc
	v_cndmask_b32_e32 v174, v53, v54, vcc
	v_lshlrev_b64 v[172:173], 10, v[172:173]
	v_lshl_add_u64 v[172:173], v[174:175], 0, v[172:173]
	v_lshl_add_u64 v[172:173], v[172:173], 0, v[118:119]
	v_lshl_add_u64 v[172:173], v[172:173], 0, v[214:215]
	global_load_dwordx4 v[64:67], v[172:173], off
	v_and_b32_e32 v172, 2.0, v47
	v_cmp_eq_u32_e32 vcc, 0, v172
	v_and_b32_e32 v172, 0xffff, v47
	v_ashrrev_i32_e32 v175, 31, v47
	v_mov_b32_e32 v173, v215
	v_lshl_add_u64 v[172:173], s[0:1], 0, v[172:173]
	v_cndmask_b32_e32 v173, v173, v175, vcc
	v_cndmask_b32_e32 v172, v172, v47, vcc
	v_cndmask_b32_e32 v175, v51, v52, vcc
	v_cndmask_b32_e32 v174, v53, v54, vcc
; #define LAS __attribute__((address_space(3)))
; __device__ __forceinline__ void sdsa2_phase(const Grp& g, LAS unsigned char* shm, int G, int tid) {
;     ...
;         { const int n = tid >> 7, kg = (tid >> 4) & 7, d4 = tid & 15; const LAS float* p0 = P + (2 * n) * 256; const LAS float* p1 = p0 + 256; float4 a0 = make_float4(0.f, 0.f, 0.f, 0.f), a1 = a0;
; #pragma unroll 16
;           for (int jj = 0; jj < 32; ++jj) { const int j = kg * 32 + jj, jc = j < ns ? j : ns - 1; const int sr = sel[jc];
;               const float* vr = (sr & 0x40000000) ? g.AV + ((size_t)db * g.L + (sr & 0xffff)) * KVW : g.cache_v + (size_t)sr * KVW;
;               const float4 vv = *(const float4*)(vr + n * 64 + 4 * d4); const float w0 = p0[j], w1 = p1[j];
;               a0.x = fmaf(w0, vv.x, a0.x); a0.y = fmaf(w0, vv.y, a0.y); a0.z = fmaf(w0, vv.z, a0.z); a0.w = fmaf(w0, vv.w, a0.w); a1.x = fmaf(w1, vv.x, a1.x); a1.y = fmaf(w1, vv.y, a1.y); a1.z = fmaf(w1, vv.z, a1.z); a1.w = fmaf(w1, vv.w, a1.w); }
	v_lshlrev_b64 v[172:173], 10, v[172:173]
	v_lshl_add_u64 v[172:173], v[174:175], 0, v[172:173]
	v_lshl_add_u64 v[172:173], v[172:173], 0, v[118:119]
	v_lshl_add_u64 v[172:173], v[172:173], 0, v[214:215]
	global_load_dwordx4 v[68:71], v[172:173], off
	v_and_b32_e32 v172, 2.0, v48
	v_cmp_eq_u32_e32 vcc, 0, v172
	v_and_b32_e32 v172, 0xffff, v48
	v_ashrrev_i32_e32 v175, 31, v48
	v_mov_b32_e32 v173, v215
	v_lshl_add_u64 v[172:173], s[0:1], 0, v[172:173]
	v_cndmask_b32_e32 v173, v173, v175, vcc
	v_cndmask_b32_e32 v172, v172, v48, vcc
	v_cndmask_b32_e32 v175, v51, v52, vcc
	v_cndmask_b32_e32 v174, v53, v54, vcc
	v_lshlrev_b64 v[172:173], 10, v[172:173]
	v_lshl_add_u64 v[172:173], v[174:175], 0, v[172:173]
	v_lshl_add_u64 v[172:173], v[172:173], 0, v[118:119]
	v_lshl_add_u64 v[172:173], v[172:173], 0, v[214:215]
	global_load_dwordx4 v[72:75], v[172:173], off
	v_and_b32_e32 v172, 2.0, v49
	v_cmp_eq_u32_e32 vcc, 0, v172
	v_and_b32_e32 v172, 0xffff, v49
	v_ashrrev_i32_e32 v175, 31, v49
	v_mov_b32_e32 v173, v215
	v_lshl_add_u64 v[172:173], s[0:1], 0, v[172:173]
	v_cndmask_b32_e32 v173, v173, v175, vcc
	v_cndmask_b32_e32 v172, v172, v49, vcc
	v_cndmask_b32_e32 v175, v51, v52, vcc
	v_cndmask_b32_e32 v174, v53, v54, vcc
	v_lshlrev_b64 v[172:173], 10, v[172:173]
	v_lshl_add_u64 v[172:173], v[174:175], 0, v[172:173]
	v_lshl_add_u64 v[172:173], v[172:173], 0, v[118:119]
	v_lshl_add_u64 v[172:173], v[172:173], 0, v[214:215]
	global_load_dwordx4 v[76:79], v[172:173], off
	v_and_b32_e32 v172, 2.0, v56
	v_cmp_eq_u32_e32 vcc, 0, v172
	v_and_b32_e32 v172, 0xffff, v56
	v_ashrrev_i32_e32 v175, 31, v56
	v_mov_b32_e32 v173, v215
	v_lshl_add_u64 v[172:173], s[0:1], 0, v[172:173]
	v_cndmask_b32_e32 v173, v173, v175, vcc
	v_cndmask_b32_e32 v172, v172, v56, vcc
	v_cndmask_b32_e32 v175, v51, v52, vcc
	v_cndmask_b32_e32 v174, v53, v54, vcc
	v_lshlrev_b64 v[172:173], 10, v[172:173]
	v_lshl_add_u64 v[172:173], v[174:175], 0, v[172:173]
	v_lshl_add_u64 v[172:173], v[172:173], 0, v[118:119]
	v_lshl_add_u64 v[172:173], v[172:173], 0, v[214:215]
	global_load_dwordx4 v[80:83], v[172:173], off
	v_and_b32_e32 v172, 2.0, v57
	v_cmp_eq_u32_e32 vcc, 0, v172
	v_and_b32_e32 v172, 0xffff, v57
	v_ashrrev_i32_e32 v175, 31, v57
	v_mov_b32_e32 v173, v215
	v_lshl_add_u64 v[172:173], s[0:1], 0, v[172:173]
	v_cndmask_b32_e32 v173, v173, v175, vcc
	v_cndmask_b32_e32 v172, v172, v57, vcc
	v_cndmask_b32_e32 v175, v51, v52, vcc
	v_cndmask_b32_e32 v174, v53, v54, vcc
	v_lshlrev_b64 v[172:173], 10, v[172:173]
	v_lshl_add_u64 v[172:173], v[174:175], 0, v[172:173]
	v_lshl_add_u64 v[172:173], v[172:173], 0, v[118:119]
	v_lshl_add_u64 v[172:173], v[172:173], 0, v[214:215]
	global_load_dwordx4 v[84:87], v[172:173], off
	v_and_b32_e32 v172, 2.0, v58
	v_cmp_eq_u32_e32 vcc, 0, v172
	v_and_b32_e32 v172, 0xffff, v58
	v_ashrrev_i32_e32 v175, 31, v58
	v_mov_b32_e32 v173, v215
	v_lshl_add_u64 v[172:173], s[0:1], 0, v[172:173]
	v_cndmask_b32_e32 v173, v173, v175, vcc
	v_cndmask_b32_e32 v172, v172, v58, vcc
	v_cndmask_b32_e32 v175, v51, v52, vcc
	v_cndmask_b32_e32 v174, v53, v54, vcc
	v_lshlrev_b64 v[172:173], 10, v[172:173]
	v_lshl_add_u64 v[172:173], v[174:175], 0, v[172:173]
	v_lshl_add_u64 v[172:173], v[172:173], 0, v[118:119]
	v_lshl_add_u64 v[172:173], v[172:173], 0, v[214:215]
	global_load_dwordx4 v[88:91], v[172:173], off
	v_and_b32_e32 v172, 2.0, v59
	v_cmp_eq_u32_e32 vcc, 0, v172
	v_and_b32_e32 v172, 0xffff, v59
	v_ashrrev_i32_e32 v175, 31, v59
	v_mov_b32_e32 v173, v215
	v_lshl_add_u64 v[172:173], s[0:1], 0, v[172:173]
	v_cndmask_b32_e32 v173, v173, v175, vcc
	v_cndmask_b32_e32 v172, v172, v59, vcc
	v_cndmask_b32_e32 v175, v51, v52, vcc
	v_cndmask_b32_e32 v174, v53, v54, vcc
	v_lshlrev_b64 v[172:173], 10, v[172:173]
	v_lshl_add_u64 v[172:173], v[174:175], 0, v[172:173]
	v_lshl_add_u64 v[172:173], v[172:173], 0, v[118:119]
	v_lshl_add_u64 v[172:173], v[172:173], 0, v[214:215]
	global_load_dwordx4 v[92:95], v[172:173], off
	v_and_b32_e32 v172, 2.0, v60
	v_cmp_eq_u32_e32 vcc, 0, v172
	v_and_b32_e32 v172, 0xffff, v60
	v_ashrrev_i32_e32 v175, 31, v60
	v_mov_b32_e32 v173, v215
	v_lshl_add_u64 v[172:173], s[0:1], 0, v[172:173]
	v_cndmask_b32_e32 v173, v173, v175, vcc
	v_cndmask_b32_e32 v172, v172, v60, vcc
	v_cndmask_b32_e32 v175, v51, v52, vcc
	v_cndmask_b32_e32 v174, v53, v54, vcc
	v_lshlrev_b64 v[172:173], 10, v[172:173]
	v_lshl_add_u64 v[172:173], v[174:175], 0, v[172:173]
	v_lshl_add_u64 v[172:173], v[172:173], 0, v[118:119]
	v_lshl_add_u64 v[172:173], v[172:173], 0, v[214:215]
	global_load_dwordx4 v[96:99], v[172:173], off
	v_and_b32_e32 v172, 2.0, v61
	v_cmp_eq_u32_e32 vcc, 0, v172
	v_and_b32_e32 v172, 0xffff, v61
	v_ashrrev_i32_e32 v175, 31, v61
	v_mov_b32_e32 v173, v215
	v_lshl_add_u64 v[172:173], s[0:1], 0, v[172:173]
	v_cndmask_b32_e32 v173, v173, v175, vcc
	v_cndmask_b32_e32 v172, v172, v61, vcc
	v_cndmask_b32_e32 v175, v51, v52, vcc
	v_cndmask_b32_e32 v174, v53, v54, vcc
	v_lshlrev_b64 v[172:173], 10, v[172:173]
	v_lshl_add_u64 v[172:173], v[174:175], 0, v[172:173]
	v_lshl_add_u64 v[172:173], v[172:173], 0, v[118:119]
	v_lshl_add_u64 v[172:173], v[172:173], 0, v[214:215]
	global_load_dwordx4 v[156:159], v[172:173], off
	v_and_b32_e32 v172, 2.0, v62
	v_cmp_eq_u32_e32 vcc, 0, v172
	v_and_b32_e32 v172, 0xffff, v62
	v_ashrrev_i32_e32 v175, 31, v62
	v_mov_b32_e32 v173, v215
	v_lshl_add_u64 v[172:173], s[0:1], 0, v[172:173]
	v_cndmask_b32_e32 v173, v173, v175, vcc
	v_cndmask_b32_e32 v172, v172, v62, vcc
	v_cndmask_b32_e32 v175, v51, v52, vcc
	v_cndmask_b32_e32 v174, v53, v54, vcc
	v_lshlrev_b64 v[172:173], 10, v[172:173]
	v_lshl_add_u64 v[172:173], v[174:175], 0, v[172:173]
	v_lshl_add_u64 v[172:173], v[172:173], 0, v[118:119]
	v_lshl_add_u64 v[172:173], v[172:173], 0, v[214:215]
	global_load_dwordx4 v[160:163], v[172:173], off
	v_and_b32_e32 v172, 2.0, v63
	v_cmp_eq_u32_e32 vcc, 0, v172
	v_and_b32_e32 v172, 0xffff, v63
	v_ashrrev_i32_e32 v175, 31, v63
	v_mov_b32_e32 v173, v215
	v_lshl_add_u64 v[172:173], s[0:1], 0, v[172:173]
	v_cndmask_b32_e32 v173, v173, v175, vcc
	v_cndmask_b32_e32 v172, v172, v63, vcc
	v_cndmask_b32_e32 v175, v51, v52, vcc
	v_cndmask_b32_e32 v174, v53, v54, vcc
	v_lshlrev_b64 v[172:173], 10, v[172:173]
	v_lshl_add_u64 v[172:173], v[174:175], 0, v[172:173]
	v_lshl_add_u64 v[172:173], v[172:173], 0, v[118:119]
	v_lshl_add_u64 v[172:173], v[172:173], 0, v[214:215]
	global_load_dwordx4 v[164:167], v[172:173], off
	ds_read_b128 v[42:45], v50
	ds_read_b128 v[46:49], v50 offset:16
	ds_read_b128 v[56:59], v50 offset:32
	ds_read_b128 v[60:63], v50 offset:48
	ds_read_b128 v[22:25], v50 offset:1024
	ds_read_b128 v[26:29], v50 offset:1040
	ds_read_b128 v[34:37], v50 offset:1056
	ds_read_b128 v[168:171], v50 offset:1072
	s_waitcnt lgkmcnt(0)
; #define LAS __attribute__((address_space(3)))
; __device__ __forceinline__ void sdsa2_phase(const Grp& g, LAS unsigned char* shm, int G, int tid) {
;     ...
;         { const int n = tid >> 7, kg = (tid >> 4) & 7, d4 = tid & 15; const LAS float* p0 = P + (2 * n) * 256; const LAS float* p1 = p0 + 256; float4 a0 = make_float4(0.f, 0.f, 0.f, 0.f), a1 = a0;
; #pragma unroll 16
;           for (int jj = 0; jj < 32; ++jj) { const int j = kg * 32 + jj, jc = j < ns ? j : ns - 1; const int sr = sel[jc];
;               const float* vr = (sr & 0x40000000) ? g.AV + ((size_t)db * g.L + (sr & 0xffff)) * KVW : g.cache_v + (size_t)sr * KVW;
;               const float4 vv = *(const float4*)(vr + n * 64 + 4 * d4); const float w0 = p0[j], w1 = p1[j];
;               a0.x = fmaf(w0, vv.x, a0.x); a0.y = fmaf(w0, vv.y, a0.y); a0.z = fmaf(w0, vv.z, a0.z); a0.w = fmaf(w0, vv.w, a0.w); a1.x = fmaf(w1, vv.x, a1.x); a1.y = fmaf(w1, vv.y, a1.y); a1.z = fmaf(w1, vv.z, a1.z); a1.w = fmaf(w1, vv.w, a1.w); }
;           *(LAS f32x4*)(red + (kg * 8 + 2 * n) * 64 + 4 * d4) = (f32x4){a0.x, a0.y, a0.z, a0.w}; *(LAS f32x4*)(red + (kg * 8 + 2 * n + 1) * 64 + 4 * d4) = (f32x4){a1.x, a1.y, a1.z, a1.w}; }
;         __syncthreads();
;         { float o = 0.f;
; #pragma unroll
;           for (int kg = 0; kg < 8; ++kg) o += red[kg * 512 + tid];
;           g.YCAT[(size_t)row * D + 512 + tid] = o; }
	s_waitcnt vmcnt(15)
	v_pk_fma_f32 v[30:31], v[42:43], v[2:3], v[30:31] op_sel_hi:[0,1,1]
	v_pk_fma_f32 v[32:33], v[42:43], v[4:5], v[32:33] op_sel_hi:[0,1,1]
	v_pk_fma_f32 v[38:39], v[22:23], v[2:3], v[38:39] op_sel_hi:[0,1,1]
	v_pk_fma_f32 v[40:41], v[22:23], v[4:5], v[40:41] op_sel_hi:[0,1,1]
	s_waitcnt vmcnt(14)
	v_pk_fma_f32 v[30:31], v[42:43], v[6:7], v[30:31] op_sel:[1,0,0]
	v_pk_fma_f32 v[32:33], v[42:43], v[8:9], v[32:33] op_sel:[1,0,0]
	v_pk_fma_f32 v[38:39], v[22:23], v[6:7], v[38:39] op_sel:[1,0,0]
	v_pk_fma_f32 v[40:41], v[22:23], v[8:9], v[40:41] op_sel:[1,0,0]
	s_waitcnt vmcnt(13)
	v_pk_fma_f32 v[30:31], v[44:45], v[10:11], v[30:31] op_sel_hi:[0,1,1]
	v_pk_fma_f32 v[32:33], v[44:45], v[12:13], v[32:33] op_sel_hi:[0,1,1]
	v_pk_fma_f32 v[38:39], v[24:25], v[10:11], v[38:39] op_sel_hi:[0,1,1]
	v_pk_fma_f32 v[40:41], v[24:25], v[12:13], v[40:41] op_sel_hi:[0,1,1]
	s_waitcnt vmcnt(12)
	v_pk_fma_f32 v[30:31], v[44:45], v[14:15], v[30:31] op_sel:[1,0,0]
	v_pk_fma_f32 v[32:33], v[44:45], v[16:17], v[32:33] op_sel:[1,0,0]
	v_pk_fma_f32 v[38:39], v[24:25], v[14:15], v[38:39] op_sel:[1,0,0]
	v_pk_fma_f32 v[40:41], v[24:25], v[16:17], v[40:41] op_sel:[1,0,0]
	s_waitcnt vmcnt(11)
	v_pk_fma_f32 v[30:31], v[46:47], v[64:65], v[30:31] op_sel_hi:[0,1,1]
	v_pk_fma_f32 v[32:33], v[46:47], v[66:67], v[32:33] op_sel_hi:[0,1,1]
	v_pk_fma_f32 v[38:39], v[26:27], v[64:65], v[38:39] op_sel_hi:[0,1,1]
	v_pk_fma_f32 v[40:41], v[26:27], v[66:67], v[40:41] op_sel_hi:[0,1,1]
	s_waitcnt vmcnt(10)
	v_pk_fma_f32 v[30:31], v[46:47], v[68:69], v[30:31] op_sel:[1,0,0]
	v_pk_fma_f32 v[32:33], v[46:47], v[70:71], v[32:33] op_sel:[1,0,0]
	v_pk_fma_f32 v[38:39], v[26:27], v[68:69], v[38:39] op_sel:[1,0,0]
	v_pk_fma_f32 v[40:41], v[26:27], v[70:71], v[40:41] op_sel:[1,0,0]
	s_waitcnt vmcnt(9)
	v_pk_fma_f32 v[30:31], v[48:49], v[72:73], v[30:31] op_sel_hi:[0,1,1]
	v_pk_fma_f32 v[32:33], v[48:49], v[74:75], v[32:33] op_sel_hi:[0,1,1]
	v_pk_fma_f32 v[38:39], v[28:29], v[72:73], v[38:39] op_sel_hi:[0,1,1]
	v_pk_fma_f32 v[40:41], v[28:29], v[74:75], v[40:41] op_sel_hi:[0,1,1]
	s_waitcnt vmcnt(8)
	v_pk_fma_f32 v[30:31], v[48:49], v[76:77], v[30:31] op_sel:[1,0,0]
	v_pk_fma_f32 v[32:33], v[48:49], v[78:79], v[32:33] op_sel:[1,0,0]
	v_pk_fma_f32 v[38:39], v[28:29], v[76:77], v[38:39] op_sel:[1,0,0]
	v_pk_fma_f32 v[40:41], v[28:29], v[78:79], v[40:41] op_sel:[1,0,0]
	s_waitcnt vmcnt(7)
	v_pk_fma_f32 v[30:31], v[56:57], v[80:81], v[30:31] op_sel_hi:[0,1,1]
	v_pk_fma_f32 v[32:33], v[56:57], v[82:83], v[32:33] op_sel_hi:[0,1,1]
	v_pk_fma_f32 v[38:39], v[34:35], v[80:81], v[38:39] op_sel_hi:[0,1,1]
	v_pk_fma_f32 v[40:41], v[34:35], v[82:83], v[40:41] op_sel_hi:[0,1,1]
	s_waitcnt vmcnt(6)
	v_pk_fma_f32 v[30:31], v[56:57], v[84:85], v[30:31] op_sel:[1,0,0]
	v_pk_fma_f32 v[32:33], v[56:57], v[86:87], v[32:33] op_sel:[1,0,0]
	v_pk_fma_f32 v[38:39], v[34:35], v[84:85], v[38:39] op_sel:[1,0,0]
	v_pk_fma_f32 v[40:41], v[34:35], v[86:87], v[40:41] op_sel:[1,0,0]
	s_waitcnt vmcnt(5)
	v_pk_fma_f32 v[30:31], v[58:59], v[88:89], v[30:31] op_sel_hi:[0,1,1]
	v_pk_fma_f32 v[32:33], v[58:59], v[90:91], v[32:33] op_sel_hi:[0,1,1]
	v_pk_fma_f32 v[38:39], v[36:37], v[88:89], v[38:39] op_sel_hi:[0,1,1]
	v_pk_fma_f32 v[40:41], v[36:37], v[90:91], v[40:41] op_sel_hi:[0,1,1]
	s_waitcnt vmcnt(4)
	v_pk_fma_f32 v[30:31], v[58:59], v[92:93], v[30:31] op_sel:[1,0,0]
	v_pk_fma_f32 v[32:33], v[58:59], v[94:95], v[32:33] op_sel:[1,0,0]
	v_pk_fma_f32 v[38:39], v[36:37], v[92:93], v[38:39] op_sel:[1,0,0]
	v_pk_fma_f32 v[40:41], v[36:37], v[94:95], v[40:41] op_sel:[1,0,0]
	s_waitcnt vmcnt(3)
	v_pk_fma_f32 v[30:31], v[60:61], v[96:97], v[30:31] op_sel_hi:[0,1,1]
	v_pk_fma_f32 v[32:33], v[60:61], v[98:99], v[32:33] op_sel_hi:[0,1,1]
	v_pk_fma_f32 v[38:39], v[168:169], v[96:97], v[38:39] op_sel_hi:[0,1,1]
	v_pk_fma_f32 v[40:41], v[168:169], v[98:99], v[40:41] op_sel_hi:[0,1,1]
	s_waitcnt vmcnt(2)
	v_pk_fma_f32 v[30:31], v[60:61], v[156:157], v[30:31] op_sel:[1,0,0]
	v_pk_fma_f32 v[32:33], v[60:61], v[158:159], v[32:33] op_sel:[1,0,0]
	v_pk_fma_f32 v[38:39], v[168:169], v[156:157], v[38:39] op_sel:[1,0,0]
	v_pk_fma_f32 v[40:41], v[168:169], v[158:159], v[40:41] op_sel:[1,0,0]
	s_waitcnt vmcnt(1)
	v_pk_fma_f32 v[30:31], v[62:63], v[160:161], v[30:31] op_sel_hi:[0,1,1]
	v_pk_fma_f32 v[32:33], v[62:63], v[162:163], v[32:33] op_sel_hi:[0,1,1]
	v_pk_fma_f32 v[38:39], v[170:171], v[160:161], v[38:39] op_sel_hi:[0,1,1]
	v_pk_fma_f32 v[40:41], v[170:171], v[162:163], v[40:41] op_sel_hi:[0,1,1]
	s_waitcnt vmcnt(0)
	v_pk_fma_f32 v[30:31], v[62:63], v[164:165], v[30:31] op_sel:[1,0,0]
	v_pk_fma_f32 v[32:33], v[62:63], v[166:167], v[32:33] op_sel:[1,0,0]
	v_pk_fma_f32 v[38:39], v[170:171], v[164:165], v[38:39] op_sel:[1,0,0]
	v_pk_fma_f32 v[40:41], v[170:171], v[166:167], v[40:41] op_sel:[1,0,0]
	v_add_u32_e32 v50, 64, v50
	s_add_i32 s2, s2, 16
	s_cmp_eq_u32 s2, 32
	s_cbranch_scc0 .LBB0_1221
	v_add_u32_e32 v28, 64, v120
	ds_write_b128 v144, v[30:33] offset:46400
	ds_write_b128 v144, v[38:41] offset:46656
	s_waitcnt lgkmcnt(0)
	s_barrier
	ds_read2st64_b32 v[22:23], v28 offset0:181 offset1:189
	ds_read2st64_b32 v[24:25], v28 offset0:197 offset1:205
	ds_read2st64_b32 v[26:27], v28 offset0:213 offset1:221
	v_readlane_b32 s52, v249, 4
	s_lshl_b64 s[0:1], s[6:7], 12
	s_waitcnt lgkmcnt(2)
	v_add_f32_e32 v22, 0, v22
	v_add_f32_e32 v29, v22, v23
	ds_read2st64_b32 v[22:23], v28 offset0:229 offset1:237
	s_waitcnt lgkmcnt(2)
	v_add_f32_e32 v24, v29, v24
	v_add_f32_e32 v24, v24, v25
	s_waitcnt lgkmcnt(1)
	v_add_f32_e32 v24, v24, v26
	v_readlane_b32 s54, v249, 6
	v_add_f32_e32 v24, v24, v27
	v_readlane_b32 s55, v249, 7
	s_add_u32 s0, s54, s0
	s_waitcnt lgkmcnt(0)
	v_add_f32_e32 v22, v24, v22
	s_addc_u32 s1, s55, s1
	v_add_f32_e32 v24, v22, v23
	v_lshl_add_u64 v[22:23], v[102:103], 2, s[0:1]
	v_add_co_u32_e32 v22, vcc, 0x5789d000, v22
	s_add_i32 s6, s6, s68
	s_nop 0
	v_addc_co_u32_e32 v23, vcc, 0, v23, vcc
	s_cmpk_gt_i32 s6, 0xff
	v_readlane_b32 s53, v249, 5
	global_store_dword v[22:23], v24, off offset:2048
	s_barrier
	s_cbranch_scc0 .LBB0_1090
	v_readlane_b32 s70, v250, 14
	v_readlane_b32 s76, v254, 15
	v_readlane_b32 s71, v250, 15
	v_readlane_b32 s72, v254, 23
	v_readlane_b32 s74, v254, 25
	v_readlane_b32 s78, v254, 27
	v_readlane_b32 s80, v254, 29
	v_readlane_b32 s82, v254, 31
	v_readlane_b32 s84, v254, 33
	v_readlane_b32 s94, v254, 35
	v_readlane_b32 s96, v254, 37
	v_readlane_b32 s44, v254, 11
	v_readlane_b32 s77, v254, 16
	v_readlane_b32 s71, v254, 22
	v_readlane_b32 s73, v254, 24
	v_readlane_b32 s75, v254, 26
	v_readlane_b32 s79, v254, 28
	v_readlane_b32 s81, v254, 30
	v_readlane_b32 s83, v254, 32
	v_readlane_b32 s85, v254, 34
	v_readlane_b32 s95, v254, 36
	v_readlane_b32 s97, v254, 38
	v_readlane_b32 s45, v254, 12
	v_readlane_b32 s46, v254, 13
	v_readlane_b32 s47, v254, 14
